# attention: touch-prefetch of gate rows and next unit Q rows into L2 at end of unit prologue
# baseline (speedup 1.0000x reference)
.LBB0_692:
	v_lshrrev_b32_e32 v2, 1, v146
	v_lshl_add_u32 v2, v168, 2, v2
	v_add_u32_e32 v2, v159, v2
	v_mul_lo_u32 v2, v2, s97
	v_and_b32_e32 v3, 1, v146
	v_lshlrev_b32_e32 v3, 7, v3
	v_lshl_add_u32 v3, v160, 1, v3
	v_add_u32_e32 v2, v2, v3
	v_add_u32_e32 v3, 0x1400, v2
	global_load_dword v253, v3, s[0:1]
	global_load_dword v253, v3, s[0:1] offset:64
	v_add_u32_e32 v4, 0xb0800, v2
	global_load_dword v253, v4, s[0:1]
	global_load_dword v253, v4, s[0:1] offset:64
	s_and_b32 s9, s12, 31
	s_and_b32 s8, s13, 0xfffff800
	s_lshl_b32 s9, s9, 6
	v_mul_f32_e32 v157, 0x3fb8aa3b, v68
	v_max_f32_e32 v0, v166, v166
	s_or_b32 s8, s9, s8
	v_max_f32_e32 v206, v0, v157
	v_add_u32_e32 v0, s8, v167
	v_mad_i64_i32 v[0:1], s[8:9], v0, s97, 0
	s_lshl_b32 s8, s11, 3
	s_and_b32 s16, s8, 0x100
	s_lshl_b32 s8, s14, 6
	v_add_u32_e32 v207, s8, v203
	v_mad_i64_i32 v[0:1], s[8:9], s8, v227, v[0:1]
	v_or_b32_e32 v0, s16, v0
	v_mov_b32_e32 v208, 0
	v_lshl_add_u64 v[162:163], v[154:155], 0, v[0:1]
	s_mov_b32 s16, 0
	v_mov_b32_e32 v34, 0
	v_mov_b32_e32 v35, v208
	v_mov_b32_e32 v36, v208
	v_mov_b32_e32 v37, v208
	v_mov_b32_e32 v38, v208
	v_mov_b32_e32 v39, v208
	v_mov_b32_e32 v40, v208
	v_mov_b32_e32 v41, v208
	v_mov_b32_e32 v42, v208
	v_mov_b32_e32 v43, v208
	v_mov_b32_e32 v44, v208
	v_mov_b32_e32 v45, v208
	v_mov_b32_e32 v46, v208
	v_mov_b32_e32 v47, v208
	v_mov_b32_e32 v48, v208
	v_mov_b32_e32 v49, v208
	v_mov_b32_e32 v50, 0
	v_mov_b32_e32 v51, v208
	v_mov_b32_e32 v52, v208
	v_mov_b32_e32 v53, v208
	v_mov_b32_e32 v54, v208
	v_mov_b32_e32 v55, v208
	v_mov_b32_e32 v56, v208
	v_mov_b32_e32 v57, v208
	v_mov_b32_e32 v58, v208
	v_mov_b32_e32 v59, v208
	v_mov_b32_e32 v60, v208
	v_mov_b32_e32 v61, v208
	v_mov_b32_e32 v62, v208
	v_mov_b32_e32 v63, v208
	v_mov_b32_e32 v64, v208
	v_mov_b32_e32 v65, v208
	v_mov_b32_e32 v66, 0
	v_mov_b32_e32 v67, v208
	v_mov_b32_e32 v68, v208
	v_mov_b32_e32 v69, v208
	v_mov_b32_e32 v70, v208
	v_mov_b32_e32 v71, v208
	v_mov_b32_e32 v72, v208
	v_mov_b32_e32 v73, v208
	v_mov_b32_e32 v74, v208
	v_mov_b32_e32 v75, v208
	v_mov_b32_e32 v76, v208
	v_mov_b32_e32 v77, v208
	v_mov_b32_e32 v78, v208
	v_mov_b32_e32 v79, v208
	v_mov_b32_e32 v80, v208
	v_mov_b32_e32 v81, v208
	v_mov_b32_e32 v82, 0
	v_mov_b32_e32 v83, v208
	v_mov_b32_e32 v84, v208
	v_mov_b32_e32 v85, v208
	v_mov_b32_e32 v86, v208
	v_mov_b32_e32 v87, v208
	v_mov_b32_e32 v88, v208
	v_mov_b32_e32 v89, v208
	v_mov_b32_e32 v90, v208
	v_mov_b32_e32 v91, v208
	v_mov_b32_e32 v92, v208
	v_mov_b32_e32 v93, v208
	v_mov_b32_e32 v94, v208
	v_mov_b32_e32 v95, v208
	v_mov_b32_e32 v96, v208
	v_mov_b32_e32 v97, v208
	s_waitcnt lgkmcnt(0)
	s_barrier
